# diff2: early uniform-bias reads moved under the last MFMA group of the preceding segment (on top of v27)
# speedup vs baseline: 1.0249x; 1.0032x over previous
; __device__ __forceinline__ void d2_qk(const LAS unsigned char* Kb, const v8s (&Q)[4], v16f& S) {
;     const v16f z = {0.f, 0.f, 0.f, 0.f, 0.f, 0.f, 0.f, 0.f, 0.f, 0.f, 0.f, 0.f, 0.f, 0.f, 0.f, 0.f};
;     const v8s k0 = *(const LAS v8s*)Kb, k1 = *(const LAS v8s*)(Kb + 32), k2 = *(const LAS v8s*)(Kb + 64), k3 = *(const LAS v8s*)(Kb + 96);
;     __builtin_amdgcn_sched_barrier(0);
;     S = MFMA32(k0, Q[0], z); S = MFMA32(k1, Q[1], S); S = MFMA32(k2, Q[2], S); S = MFMA32(k3, Q[3], S);
;     __builtin_amdgcn_sched_barrier(0);
; }
; __device__ __forceinline__ void d2_softmax(v16f& S, const float c1, const LAS float* tp, float& m, float& l, v16f (&O)[4], v8s (&P)[2]) {
;     float tmax = NEGBIG;
; #pragma unroll
;     for (int i = 0; i < 16; ++i) { S[i] = S[i] * c1 + tp[(i & 3) + 8 * (i >> 2)]; tmax = fmaxf(tmax, S[i]); }
;     tmax = fmaxf(tmax, __shfl_xor(tmax, 32));
;     const float mo = m;
;     if (__any(tmax > mo + 8.f)) {
;         const float mn = (tmax > mo + 8.f) ? tmax : mo;
;         const float alpha = __builtin_amdgcn_exp2f(mo - mn);
;         l *= alpha;
; #pragma unroll
;         for (int eb = 0; eb < 4; ++eb)
; #pragma unroll
;             for (int i = 0; i < 16; ++i) O[eb][i] *= alpha;
;         m = mn;
;     }
;     const float mc = m;
;     float ps = 0.f;
; #pragma unroll
;     for (int i = 0; i < 16; ++i) { S[i] = __builtin_amdgcn_exp2f(S[i] - mc); ps += S[i]; }
;     l += ps;
; #pragma unroll
;     for (int s2 = 0; s2 < 2; ++s2) { v4u w; w.x = pk2(S[8 * s2 + 0], S[8 * s2 + 1]); w.y = pk2(S[8 * s2 + 2], S[8 * s2 + 3]); w.z = pk2(S[8 * s2 + 4], S[8 * s2 + 5]); w.w = pk2(S[8 * s2 + 6], S[8 * s2 + 7]);
;         P[s2] = __builtin_bit_cast(v8s, w); }
; }
; __device__ __forceinline__ void d2_pv(const LAS unsigned char* vb0, const v8s (&P)[2], v16f (&O)[4]) {
;     const LAS unsigned char* va = vb0; const LAS unsigned char* vc = vb0 + 16 * 320;
;     const v4s l0 = TRR(va), h0 = TRR(va + 2560), l1 = TRR(va + 64), h1 = TRR(va + 2624), l2 = TRR(va + 128), h2 = TRR(va + 2688), l3 = TRR(va + 192), h3 = TRR(va + 2752);
;     __builtin_amdgcn_sched_barrier(0);
;     const v4s m0 = TRR(vc), n0 = TRR(vc + 2560), m1 = TRR(vc + 64), n1 = TRR(vc + 2624), m2 = TRR(vc + 128), n2 = TRR(vc + 2688), m3 = TRR(vc + 192), n3 = TRR(vc + 2752);
;     O[0] = MFMA32(__builtin_shufflevector(l0, h0, 0, 1, 2, 3, 4, 5, 6, 7), P[0], O[0]);
.LBB0_333:
	s_mul_i32 s19, s18, 0x4800
	v_add_u32_e32 v0, s19, v181
	ds_read_b128 v[66:69], v0
	ds_read_b128 v[82:85], v0 offset:32
	ds_read_b128 v[86:89], v0 offset:64
	ds_read_b128 v[90:93], v0 offset:96
	s_waitcnt lgkmcnt(3)
	v_mfma_f32_32x32x16_bf16 v[66:81], v[66:69], v[98:101], 0
	s_waitcnt lgkmcnt(2)
	v_mfma_f32_32x32x16_bf16 v[66:81], v[82:85], v[102:105], v[66:81]
	s_waitcnt lgkmcnt(1)
	v_mfma_f32_32x32x16_bf16 v[66:81], v[86:89], v[106:109], v[66:81]
	s_waitcnt lgkmcnt(0)
	v_mfma_f32_32x32x16_bf16 v[66:81], v[90:93], v[110:113], v[66:81]
	ds_read_b128 v[82:85], v0 offset:4608
	ds_read_b128 v[156:159], v0 offset:4640
	ds_read_b128 v[186:189], v0 offset:4672
	ds_read_b128 v[190:193], v0 offset:4704
	s_waitcnt lgkmcnt(3)
	v_mfma_f32_32x32x16_bf16 v[82:97], v[82:85], v[98:101], 0
	s_waitcnt lgkmcnt(2)
	v_mfma_f32_32x32x16_bf16 v[82:97], v[156:159], v[102:105], v[82:97]
	s_waitcnt lgkmcnt(1)
	v_mfma_f32_32x32x16_bf16 v[82:97], v[186:189], v[106:109], v[82:97]
	s_waitcnt lgkmcnt(0)
	v_mfma_f32_32x32x16_bf16 v[82:97], v[190:193], v[110:113], v[82:97]
	s_cmp_eq_u32 s6, 0
	s_cbranch_scc1 .LBB0_335
	s_xor_b32 s18, s18, 1
	s_mulk_i32 s18, 0x5000
	v_add_u32_e32 v0, s18, v180
	ds_read_b64_tr_b16 v[156:157], v0 offset:36864
	ds_read_b64_tr_b16 v[186:187], v0 offset:36928
	ds_read_b64_tr_b16 v[190:191], v0 offset:36992
	ds_read_b64_tr_b16 v[194:195], v0 offset:37056
	ds_read_b64_tr_b16 v[158:159], v0 offset:39424
	ds_read_b64_tr_b16 v[188:189], v0 offset:39488
	ds_read_b64_tr_b16 v[192:193], v0 offset:39552
	ds_read_b64_tr_b16 v[196:197], v0 offset:39616
	s_waitcnt lgkmcnt(3)
	v_mfma_f32_32x32x16_bf16 v[50:65], v[156:159], v[134:137], v[50:65]
	s_waitcnt lgkmcnt(2)
	v_mfma_f32_32x32x16_bf16 v[34:49], v[186:189], v[134:137], v[34:49]
	s_waitcnt lgkmcnt(1)
	v_mfma_f32_32x32x16_bf16 v[18:33], v[190:193], v[134:137], v[18:33]
	ds_read_b64_tr_b16 v[156:157], v0 offset:41984
	ds_read_b64_tr_b16 v[186:187], v0 offset:42048
	ds_read_b64_tr_b16 v[190:191], v0 offset:42112
	ds_read_b64_tr_b16 v[198:199], v0 offset:42176
	ds_read_b64_tr_b16 v[158:159], v0 offset:44544
	ds_read_b64_tr_b16 v[188:189], v0 offset:44608
	ds_read_b64_tr_b16 v[192:193], v0 offset:44672
	ds_read_b64_tr_b16 v[200:201], v0 offset:44736
	s_waitcnt lgkmcnt(8)
	v_mfma_f32_32x32x16_bf16 v[2:17], v[194:197], v[134:137], v[2:17]
	s_waitcnt lgkmcnt(3)
	v_mfma_f32_32x32x16_bf16 v[50:65], v[156:159], v[130:133], v[50:65]
	s_waitcnt lgkmcnt(2)
	v_mfma_f32_32x32x16_bf16 v[34:49], v[186:189], v[130:133], v[34:49]
	s_waitcnt lgkmcnt(1)
	v_mfma_f32_32x32x16_bf16 v[18:33], v[190:193], v[130:133], v[18:33]
	s_waitcnt lgkmcnt(0)
	v_mfma_f32_32x32x16_bf16 v[2:17], v[198:201], v[130:133], v[2:17]
	ds_read_b64_tr_b16 v[156:157], v0 offset:47104
	ds_read_b64_tr_b16 v[186:187], v0 offset:47168
	ds_read_b64_tr_b16 v[190:191], v0 offset:47232
	ds_read_b64_tr_b16 v[194:195], v0 offset:47296
	ds_read_b64_tr_b16 v[158:159], v0 offset:49664
	ds_read_b64_tr_b16 v[188:189], v0 offset:49728
	ds_read_b64_tr_b16 v[192:193], v0 offset:49792
	ds_read_b64_tr_b16 v[196:197], v0 offset:49856
	s_waitcnt lgkmcnt(3)
	v_mfma_f32_32x32x16_bf16 v[50:65], v[156:159], v[142:145], v[50:65]
	s_waitcnt lgkmcnt(2)
	v_mfma_f32_32x32x16_bf16 v[34:49], v[186:189], v[142:145], v[34:49]
	s_waitcnt lgkmcnt(1)
	v_mfma_f32_32x32x16_bf16 v[18:33], v[190:193], v[142:145], v[18:33]
	v_add_u32_e32 v253, 32, v183
	v_med3_i32 v252, v183, s16, v214
	v_med3_i32 v253, v253, s16, v214
	v_lshl_add_u32 v252, v252, 2, s23
	v_lshl_add_u32 v253, v253, 2, s23
	ds_read_b32 v254, v252 offset:2688
	ds_read_b32 v255, v253 offset:2688
	ds_read_b64_tr_b16 v[156:157], v0 offset:52224
	ds_read_b64_tr_b16 v[186:187], v0 offset:52288
	ds_read_b64_tr_b16 v[190:191], v0 offset:52352
	ds_read_b64_tr_b16 v[198:199], v0 offset:52416
	ds_read_b64_tr_b16 v[158:159], v0 offset:54784
	ds_read_b64_tr_b16 v[188:189], v0 offset:54848
	ds_read_b64_tr_b16 v[192:193], v0 offset:54912
	ds_read_b64_tr_b16 v[200:201], v0 offset:54976
	s_waitcnt lgkmcnt(8)
	v_mfma_f32_32x32x16_bf16 v[2:17], v[194:197], v[142:145], v[2:17]
	s_waitcnt lgkmcnt(3)
	v_mfma_f32_32x32x16_bf16 v[50:65], v[156:159], v[138:141], v[50:65]
	s_waitcnt lgkmcnt(2)
	v_mfma_f32_32x32x16_bf16 v[34:49], v[186:189], v[138:141], v[34:49]
	s_waitcnt lgkmcnt(1)
	v_mfma_f32_32x32x16_bf16 v[18:33], v[190:193], v[138:141], v[18:33]
	s_waitcnt lgkmcnt(0)
	v_mfma_f32_32x32x16_bf16 v[2:17], v[198:201], v[138:141], v[2:17]

; #define LAS __attribute__((address_space(3)))
; #define MFMA32(a, b, c) __builtin_amdgcn_mfma_f32_32x32x16_bf16((a), (b), (c), 0, 0, 0)
; #define TRR(p_) __builtin_amdgcn_ds_read_tr16_b64_v4i16((LAS v4s*)(p_))
; __device__ __forceinline__ void d2_pv(const LAS unsigned char* vb0, const v8s (&P)[2], v16f (&O)[4]) {
;     const LAS unsigned char* va = vb0; const LAS unsigned char* vc = vb0 + 16 * 320;
;     const v4s l0 = TRR(va), h0 = TRR(va + 2560), l1 = TRR(va + 64), h1 = TRR(va + 2624), l2 = TRR(va + 128), h2 = TRR(va + 2688), l3 = TRR(va + 192), h3 = TRR(va + 2752);
;     __builtin_amdgcn_sched_barrier(0);
;     const v4s m0 = TRR(vc), n0 = TRR(vc + 2560), m1 = TRR(vc + 64), n1 = TRR(vc + 2624), m2 = TRR(vc + 128), n2 = TRR(vc + 2688), m3 = TRR(vc + 192), n3 = TRR(vc + 2752);
;     O[0] = MFMA32(__builtin_shufflevector(l0, h0, 0, 1, 2, 3, 4, 5, 6, 7), P[0], O[0]);
;     O[1] = MFMA32(__builtin_shufflevector(l1, h1, 0, 1, 2, 3, 4, 5, 6, 7), P[0], O[1]);
;     O[2] = MFMA32(__builtin_shufflevector(l2, h2, 0, 1, 2, 3, 4, 5, 6, 7), P[0], O[2]);
;     O[3] = MFMA32(__builtin_shufflevector(l3, h3, 0, 1, 2, 3, 4, 5, 6, 7), P[0], O[3]);
;     __builtin_amdgcn_sched_barrier(0);
;     O[0] = MFMA32(__builtin_shufflevector(m0, n0, 0, 1, 2, 3, 4, 5, 6, 7), P[1], O[0]);
;     O[1] = MFMA32(__builtin_shufflevector(m1, n1, 0, 1, 2, 3, 4, 5, 6, 7), P[1], O[1]);
;     O[2] = MFMA32(__builtin_shufflevector(m2, n2, 0, 1, 2, 3, 4, 5, 6, 7), P[1], O[2]);
;     O[3] = MFMA32(__builtin_shufflevector(m3, n3, 0, 1, 2, 3, 4, 5, 6, 7), P[1], O[3]);
;     __builtin_amdgcn_sched_barrier(0);
; }
.LBB0_350:
	v_add_u32_e32 v0, s28, v180
	ds_read_b64_tr_b16 v[156:157], v0 offset:36864
	ds_read_b64_tr_b16 v[186:187], v0 offset:36928
	ds_read_b64_tr_b16 v[190:191], v0 offset:36992
	ds_read_b64_tr_b16 v[194:195], v0 offset:37056
	ds_read_b64_tr_b16 v[158:159], v0 offset:39424
	ds_read_b64_tr_b16 v[188:189], v0 offset:39488
	ds_read_b64_tr_b16 v[192:193], v0 offset:39552
	ds_read_b64_tr_b16 v[196:197], v0 offset:39616
	s_waitcnt lgkmcnt(3)
	v_mfma_f32_32x32x16_bf16 v[50:65], v[156:159], v[134:137], v[50:65]
	s_waitcnt lgkmcnt(2)
	v_mfma_f32_32x32x16_bf16 v[34:49], v[186:189], v[134:137], v[34:49]
	s_waitcnt lgkmcnt(1)
	v_mfma_f32_32x32x16_bf16 v[18:33], v[190:193], v[134:137], v[18:33]
	ds_read_b64_tr_b16 v[156:157], v0 offset:41984
	ds_read_b64_tr_b16 v[186:187], v0 offset:42048
	ds_read_b64_tr_b16 v[190:191], v0 offset:42112
	ds_read_b64_tr_b16 v[198:199], v0 offset:42176
	ds_read_b64_tr_b16 v[158:159], v0 offset:44544
	ds_read_b64_tr_b16 v[188:189], v0 offset:44608
	ds_read_b64_tr_b16 v[192:193], v0 offset:44672
	ds_read_b64_tr_b16 v[200:201], v0 offset:44736
	s_waitcnt lgkmcnt(8)
	v_mfma_f32_32x32x16_bf16 v[2:17], v[194:197], v[134:137], v[2:17]
	s_waitcnt lgkmcnt(3)
	v_mfma_f32_32x32x16_bf16 v[50:65], v[156:159], v[130:133], v[50:65]
	s_waitcnt lgkmcnt(2)
	v_mfma_f32_32x32x16_bf16 v[34:49], v[186:189], v[130:133], v[34:49]
	s_waitcnt lgkmcnt(1)
	v_mfma_f32_32x32x16_bf16 v[18:33], v[190:193], v[130:133], v[18:33]
	s_waitcnt lgkmcnt(0)
	v_mfma_f32_32x32x16_bf16 v[2:17], v[198:201], v[130:133], v[2:17]
	ds_read_b64_tr_b16 v[156:157], v0 offset:47104
	ds_read_b64_tr_b16 v[186:187], v0 offset:47168
	ds_read_b64_tr_b16 v[190:191], v0 offset:47232
	ds_read_b64_tr_b16 v[194:195], v0 offset:47296
	ds_read_b64_tr_b16 v[158:159], v0 offset:49664
	ds_read_b64_tr_b16 v[188:189], v0 offset:49728
	ds_read_b64_tr_b16 v[192:193], v0 offset:49792
	ds_read_b64_tr_b16 v[196:197], v0 offset:49856
	s_waitcnt lgkmcnt(3)
	v_mfma_f32_32x32x16_bf16 v[50:65], v[156:159], v[142:145], v[50:65]
	s_waitcnt lgkmcnt(2)
	v_mfma_f32_32x32x16_bf16 v[34:49], v[186:189], v[142:145], v[34:49]
	s_waitcnt lgkmcnt(1)
	v_mfma_f32_32x32x16_bf16 v[18:33], v[190:193], v[142:145], v[18:33]
	v_add_u32_e32 v252, 64, v183
	v_add_u32_e32 v253, 96, v183
	v_med3_i32 v252, v252, s16, v214
	v_med3_i32 v253, v253, s16, v214
	v_lshl_add_u32 v252, v252, 2, s23
	v_lshl_add_u32 v253, v253, 2, s23
	ds_read_b32 v254, v252 offset:2688
	ds_read_b32 v255, v253 offset:2688
	ds_read_b64_tr_b16 v[156:157], v0 offset:52224
	ds_read_b64_tr_b16 v[186:187], v0 offset:52288
	ds_read_b64_tr_b16 v[190:191], v0 offset:52352
	ds_read_b64_tr_b16 v[198:199], v0 offset:52416
	ds_read_b64_tr_b16 v[158:159], v0 offset:54784
	ds_read_b64_tr_b16 v[188:189], v0 offset:54848
	ds_read_b64_tr_b16 v[192:193], v0 offset:54912
	ds_read_b64_tr_b16 v[200:201], v0 offset:54976
	s_waitcnt lgkmcnt(8)
	v_mfma_f32_32x32x16_bf16 v[2:17], v[194:197], v[142:145], v[2:17]
	s_waitcnt lgkmcnt(3)
	v_mfma_f32_32x32x16_bf16 v[50:65], v[156:159], v[138:141], v[50:65]
	s_waitcnt lgkmcnt(2)
	v_mfma_f32_32x32x16_bf16 v[34:49], v[186:189], v[138:141], v[34:49]
	s_waitcnt lgkmcnt(1)
	v_mfma_f32_32x32x16_bf16 v[18:33], v[190:193], v[138:141], v[18:33]
	s_waitcnt lgkmcnt(0)
	v_mfma_f32_32x32x16_bf16 v[2:17], v[198:201], v[138:141], v[2:17]
